# hand-written residual epilogues for phases G and J (batched loads, counted waits) + phase F double-buffered LDS + S5 loop waits
# speedup vs baseline: 1.0463x; 1.0463x over previous
.LBB0_718:
	s_waitcnt vmcnt(0)
	s_mulk_i32 s8, 0xc0
	v_readlane_b32 s22, v253, 53
	v_readlane_b32 s20, v253, 50
	v_and_b32_e32 v100, 0x4f, v196
	v_lshlrev_b32_e32 v100, 2, v100
	v_lshl_or_b32 v100, s19, 9, v100
	v_lshrrev_b32_e32 v101, 3, v196
	v_and_b32_e32 v101, -16, v101
	v_lshrrev_b32_e32 v102, 2, v196
	v_and_b32_e32 v102, 12, v102
	v_add3_u32 v101, v101, v102, s8
	s_lshl_b32 s20, s20, 2
	s_add_i32 s20, s20, 20480
	v_add_u32_e32 v103, s20, v100
	global_load_dword v104, v103, s[78:79]
	global_load_dword v105, v103, s[78:79] offset:64
	global_load_dword v106, v103, s[78:79] offset:128
	global_load_dword v107, v103, s[78:79] offset:192
	v_add_u32_e32 v164, 0, v101
	v_add_u32_e32 v165, 0xffffe000, v164
	v_lshrrev_b32_e32 v165, 10, v165
	v_add_u32_e32 v165, 1, v165
	v_cmp_lt_i32_e32 vcc, 0x1fff, v164
	s_nop 1
	v_cndmask_b32_e32 v165, 0, v165, vcc
	v_add_u32_e32 v165, s22, v165
	v_mul_u32_u24_e32 v165, 0x6000, v165
	v_add_u32_e32 v166, v165, v100
	v_add_u32_e32 v166, 0xe285000, v166
	global_load_dword v126, v166, s[62:63]
	global_load_dword v127, v166, s[62:63] offset:64
	global_load_dword v128, v166, s[62:63] offset:128
	global_load_dword v129, v166, s[62:63] offset:192
	v_lshl_add_u32 v136, v164, 12, v100
	v_add_u32_e32 v137, 0x1000, v136
	v_add_u32_e32 v138, 0x2000, v136
	v_add_u32_e32 v139, 0x3000, v136
	global_load_dword v110, v136, s[60:61]
	global_load_dword v111, v136, s[60:61] offset:64
	global_load_dword v112, v136, s[60:61] offset:128
	global_load_dword v113, v136, s[60:61] offset:192
	global_load_dword v114, v137, s[60:61]
	global_load_dword v115, v137, s[60:61] offset:64
	global_load_dword v116, v137, s[60:61] offset:128
	global_load_dword v117, v137, s[60:61] offset:192
	global_load_dword v118, v138, s[60:61]
	global_load_dword v119, v138, s[60:61] offset:64
	global_load_dword v120, v138, s[60:61] offset:128
	global_load_dword v121, v138, s[60:61] offset:192
	global_load_dword v122, v139, s[60:61]
	global_load_dword v123, v139, s[60:61] offset:64
	global_load_dword v124, v139, s[60:61] offset:128
	global_load_dword v125, v139, s[60:61] offset:192
	v_add_u32_e32 v164, 32, v101
	v_add_u32_e32 v165, 0xffffe000, v164
	v_lshrrev_b32_e32 v165, 10, v165
	v_add_u32_e32 v165, 1, v165
	v_cmp_lt_i32_e32 vcc, 0x1fff, v164
	s_nop 1
	v_cndmask_b32_e32 v165, 0, v165, vcc
	v_add_u32_e32 v165, s22, v165
	v_mul_u32_u24_e32 v165, 0x6000, v165
	v_add_u32_e32 v166, v165, v100
	v_add_u32_e32 v166, 0xe285000, v166
	global_load_dword v156, v166, s[62:63]
	global_load_dword v157, v166, s[62:63] offset:64
	global_load_dword v158, v166, s[62:63] offset:128
	global_load_dword v159, v166, s[62:63] offset:192
	v_lshl_add_u32 v160, v164, 12, v100
	v_add_u32_e32 v161, 0x1000, v160
	v_add_u32_e32 v162, 0x2000, v160
	v_add_u32_e32 v163, 0x3000, v160
	global_load_dword v140, v160, s[60:61]
	global_load_dword v141, v160, s[60:61] offset:64
	global_load_dword v142, v160, s[60:61] offset:128
	global_load_dword v143, v160, s[60:61] offset:192
	global_load_dword v144, v161, s[60:61]
	global_load_dword v145, v161, s[60:61] offset:64
	global_load_dword v146, v161, s[60:61] offset:128
	global_load_dword v147, v161, s[60:61] offset:192
	global_load_dword v148, v162, s[60:61]
	global_load_dword v149, v162, s[60:61] offset:64
	global_load_dword v150, v162, s[60:61] offset:128
	global_load_dword v151, v162, s[60:61] offset:192
	global_load_dword v152, v163, s[60:61]
	global_load_dword v153, v163, s[60:61] offset:64
	global_load_dword v154, v163, s[60:61] offset:128
	global_load_dword v155, v163, s[60:61] offset:192
	s_waitcnt vmcnt(20)
	v_add_f32_e32 v126, v126, v104
	v_add_f32_e32 v127, v127, v105
	v_add_f32_e32 v128, v128, v106
	v_add_f32_e32 v129, v129, v107
	v_fmac_f32_e32 v110, v132, v126
	v_fmac_f32_e32 v111, v96, v127
	v_fmac_f32_e32 v112, v92, v128
	v_fmac_f32_e32 v113, v88, v129
	v_fmac_f32_e32 v114, v133, v126
	v_fmac_f32_e32 v115, v97, v127
	v_fmac_f32_e32 v116, v93, v128
	v_fmac_f32_e32 v117, v89, v129
	v_fmac_f32_e32 v118, v134, v126
	v_fmac_f32_e32 v119, v98, v127
	v_fmac_f32_e32 v120, v94, v128
	v_fmac_f32_e32 v121, v90, v129
	v_fmac_f32_e32 v122, v135, v126
	v_fmac_f32_e32 v123, v99, v127
	v_fmac_f32_e32 v124, v95, v128
	v_fmac_f32_e32 v125, v91, v129
	global_store_dword v136, v110, s[60:61]
	global_store_dword v136, v111, s[60:61] offset:64
	global_store_dword v136, v112, s[60:61] offset:128
	global_store_dword v136, v113, s[60:61] offset:192
	global_store_dword v137, v114, s[60:61]
	global_store_dword v137, v115, s[60:61] offset:64
	global_store_dword v137, v116, s[60:61] offset:128
	global_store_dword v137, v117, s[60:61] offset:192
	global_store_dword v138, v118, s[60:61]
	global_store_dword v138, v119, s[60:61] offset:64
	global_store_dword v138, v120, s[60:61] offset:128
	global_store_dword v138, v121, s[60:61] offset:192
	global_store_dword v139, v122, s[60:61]
	global_store_dword v139, v123, s[60:61] offset:64
	global_store_dword v139, v124, s[60:61] offset:128
	global_store_dword v139, v125, s[60:61] offset:192
	v_add_u32_e32 v164, 64, v101
	v_add_u32_e32 v165, 0xffffe000, v164
	v_lshrrev_b32_e32 v165, 10, v165
	v_add_u32_e32 v165, 1, v165
	v_cmp_lt_i32_e32 vcc, 0x1fff, v164
	s_nop 1
	v_cndmask_b32_e32 v165, 0, v165, vcc
	v_add_u32_e32 v165, s22, v165
	v_mul_u32_u24_e32 v165, 0x6000, v165
	v_add_u32_e32 v166, v165, v100
	v_add_u32_e32 v166, 0xe285000, v166
	global_load_dword v126, v166, s[62:63]
	global_load_dword v127, v166, s[62:63] offset:64
	global_load_dword v128, v166, s[62:63] offset:128
	global_load_dword v129, v166, s[62:63] offset:192
	v_lshl_add_u32 v136, v164, 12, v100
	v_add_u32_e32 v137, 0x1000, v136
	v_add_u32_e32 v138, 0x2000, v136
	v_add_u32_e32 v139, 0x3000, v136
	global_load_dword v110, v136, s[60:61]
	global_load_dword v111, v136, s[60:61] offset:64
	global_load_dword v112, v136, s[60:61] offset:128
	global_load_dword v113, v136, s[60:61] offset:192
	global_load_dword v114, v137, s[60:61]
	global_load_dword v115, v137, s[60:61] offset:64
	global_load_dword v116, v137, s[60:61] offset:128
	global_load_dword v117, v137, s[60:61] offset:192
	global_load_dword v118, v138, s[60:61]
	global_load_dword v119, v138, s[60:61] offset:64
	global_load_dword v120, v138, s[60:61] offset:128
	global_load_dword v121, v138, s[60:61] offset:192
	global_load_dword v122, v139, s[60:61]
	global_load_dword v123, v139, s[60:61] offset:64
	global_load_dword v124, v139, s[60:61] offset:128
	global_load_dword v125, v139, s[60:61] offset:192
	s_waitcnt vmcnt(36)
	v_add_f32_e32 v156, v156, v104
	v_add_f32_e32 v157, v157, v105
	v_add_f32_e32 v158, v158, v106
	v_add_f32_e32 v159, v159, v107
	v_fmac_f32_e32 v140, v84, v156
	v_fmac_f32_e32 v141, v80, v157
	v_fmac_f32_e32 v142, v76, v158
	v_fmac_f32_e32 v143, v72, v159
	v_fmac_f32_e32 v144, v85, v156
	v_fmac_f32_e32 v145, v81, v157
	v_fmac_f32_e32 v146, v77, v158
	v_fmac_f32_e32 v147, v73, v159
	v_fmac_f32_e32 v148, v86, v156
	v_fmac_f32_e32 v149, v82, v157
	v_fmac_f32_e32 v150, v78, v158
	v_fmac_f32_e32 v151, v74, v159
	v_fmac_f32_e32 v152, v87, v156
	v_fmac_f32_e32 v153, v83, v157
	v_fmac_f32_e32 v154, v79, v158
	v_fmac_f32_e32 v155, v75, v159
	global_store_dword v160, v140, s[60:61]
	global_store_dword v160, v141, s[60:61] offset:64
	global_store_dword v160, v142, s[60:61] offset:128
	global_store_dword v160, v143, s[60:61] offset:192
	global_store_dword v161, v144, s[60:61]
	global_store_dword v161, v145, s[60:61] offset:64
	global_store_dword v161, v146, s[60:61] offset:128
	global_store_dword v161, v147, s[60:61] offset:192
	global_store_dword v162, v148, s[60:61]
	global_store_dword v162, v149, s[60:61] offset:64
	global_store_dword v162, v150, s[60:61] offset:128
	global_store_dword v162, v151, s[60:61] offset:192
	global_store_dword v163, v152, s[60:61]
	global_store_dword v163, v153, s[60:61] offset:64
	global_store_dword v163, v154, s[60:61] offset:128
	global_store_dword v163, v155, s[60:61] offset:192
	v_add_u32_e32 v164, 96, v101
	v_add_u32_e32 v165, 0xffffe000, v164
	v_lshrrev_b32_e32 v165, 10, v165
	v_add_u32_e32 v165, 1, v165
	v_cmp_lt_i32_e32 vcc, 0x1fff, v164
	s_nop 1
	v_cndmask_b32_e32 v165, 0, v165, vcc
	v_add_u32_e32 v165, s22, v165
	v_mul_u32_u24_e32 v165, 0x6000, v165
	v_add_u32_e32 v166, v165, v100
	v_add_u32_e32 v166, 0xe285000, v166
	global_load_dword v156, v166, s[62:63]
	global_load_dword v157, v166, s[62:63] offset:64
	global_load_dword v158, v166, s[62:63] offset:128
	global_load_dword v159, v166, s[62:63] offset:192
	v_lshl_add_u32 v160, v164, 12, v100
	v_add_u32_e32 v161, 0x1000, v160
	v_add_u32_e32 v162, 0x2000, v160
	v_add_u32_e32 v163, 0x3000, v160
	global_load_dword v140, v160, s[60:61]
	global_load_dword v141, v160, s[60:61] offset:64
	global_load_dword v142, v160, s[60:61] offset:128
	global_load_dword v143, v160, s[60:61] offset:192
	global_load_dword v144, v161, s[60:61]
	global_load_dword v145, v161, s[60:61] offset:64
	global_load_dword v146, v161, s[60:61] offset:128
	global_load_dword v147, v161, s[60:61] offset:192
	global_load_dword v148, v162, s[60:61]
	global_load_dword v149, v162, s[60:61] offset:64
	global_load_dword v150, v162, s[60:61] offset:128
	global_load_dword v151, v162, s[60:61] offset:192
	global_load_dword v152, v163, s[60:61]
	global_load_dword v153, v163, s[60:61] offset:64
	global_load_dword v154, v163, s[60:61] offset:128
	global_load_dword v155, v163, s[60:61] offset:192
	s_waitcnt vmcnt(36)
	v_add_f32_e32 v126, v126, v104
	v_add_f32_e32 v127, v127, v105
	v_add_f32_e32 v128, v128, v106
	v_add_f32_e32 v129, v129, v107
	v_fmac_f32_e32 v110, v68, v126
	v_fmac_f32_e32 v111, v64, v127
	v_fmac_f32_e32 v112, v60, v128
	v_fmac_f32_e32 v113, v56, v129
	v_fmac_f32_e32 v114, v69, v126
	v_fmac_f32_e32 v115, v65, v127
	v_fmac_f32_e32 v116, v61, v128
	v_fmac_f32_e32 v117, v57, v129
	v_fmac_f32_e32 v118, v70, v126
	v_fmac_f32_e32 v119, v66, v127
	v_fmac_f32_e32 v120, v62, v128
	v_fmac_f32_e32 v121, v58, v129
	v_fmac_f32_e32 v122, v71, v126
	v_fmac_f32_e32 v123, v67, v127
	v_fmac_f32_e32 v124, v63, v128
	v_fmac_f32_e32 v125, v59, v129
	global_store_dword v136, v110, s[60:61]
	global_store_dword v136, v111, s[60:61] offset:64
	global_store_dword v136, v112, s[60:61] offset:128
	global_store_dword v136, v113, s[60:61] offset:192
	global_store_dword v137, v114, s[60:61]
	global_store_dword v137, v115, s[60:61] offset:64
	global_store_dword v137, v116, s[60:61] offset:128
	global_store_dword v137, v117, s[60:61] offset:192
	global_store_dword v138, v118, s[60:61]
	global_store_dword v138, v119, s[60:61] offset:64
	global_store_dword v138, v120, s[60:61] offset:128
	global_store_dword v138, v121, s[60:61] offset:192
	global_store_dword v139, v122, s[60:61]
	global_store_dword v139, v123, s[60:61] offset:64
	global_store_dword v139, v124, s[60:61] offset:128
	global_store_dword v139, v125, s[60:61] offset:192
	v_add_u32_e32 v164, 128, v101
	v_add_u32_e32 v165, 0xffffe000, v164
	v_lshrrev_b32_e32 v165, 10, v165
	v_add_u32_e32 v165, 1, v165
	v_cmp_lt_i32_e32 vcc, 0x1fff, v164
	s_nop 1
	v_cndmask_b32_e32 v165, 0, v165, vcc
	v_add_u32_e32 v165, s22, v165
	v_mul_u32_u24_e32 v165, 0x6000, v165
	v_add_u32_e32 v166, v165, v100
	v_add_u32_e32 v166, 0xe285000, v166
	global_load_dword v126, v166, s[62:63]
	global_load_dword v127, v166, s[62:63] offset:64
	global_load_dword v128, v166, s[62:63] offset:128
	global_load_dword v129, v166, s[62:63] offset:192
	v_lshl_add_u32 v136, v164, 12, v100
	v_add_u32_e32 v137, 0x1000, v136
	v_add_u32_e32 v138, 0x2000, v136
	v_add_u32_e32 v139, 0x3000, v136
	global_load_dword v110, v136, s[60:61]
	global_load_dword v111, v136, s[60:61] offset:64
	global_load_dword v112, v136, s[60:61] offset:128
	global_load_dword v113, v136, s[60:61] offset:192
	global_load_dword v114, v137, s[60:61]
	global_load_dword v115, v137, s[60:61] offset:64
	global_load_dword v116, v137, s[60:61] offset:128
	global_load_dword v117, v137, s[60:61] offset:192
	global_load_dword v118, v138, s[60:61]
	global_load_dword v119, v138, s[60:61] offset:64
	global_load_dword v120, v138, s[60:61] offset:128
	global_load_dword v121, v138, s[60:61] offset:192
	global_load_dword v122, v139, s[60:61]
	global_load_dword v123, v139, s[60:61] offset:64
	global_load_dword v124, v139, s[60:61] offset:128
	global_load_dword v125, v139, s[60:61] offset:192
	s_waitcnt vmcnt(36)
	v_add_f32_e32 v156, v156, v104
	v_add_f32_e32 v157, v157, v105
	v_add_f32_e32 v158, v158, v106
	v_add_f32_e32 v159, v159, v107
	v_fmac_f32_e32 v140, v52, v156
	v_fmac_f32_e32 v141, v48, v157
	v_fmac_f32_e32 v142, v44, v158
	v_fmac_f32_e32 v143, v40, v159
	v_fmac_f32_e32 v144, v53, v156
	v_fmac_f32_e32 v145, v49, v157
	v_fmac_f32_e32 v146, v45, v158
	v_fmac_f32_e32 v147, v41, v159
	v_fmac_f32_e32 v148, v54, v156
	v_fmac_f32_e32 v149, v50, v157
	v_fmac_f32_e32 v150, v46, v158
	v_fmac_f32_e32 v151, v42, v159
	v_fmac_f32_e32 v152, v55, v156
	v_fmac_f32_e32 v153, v51, v157
	v_fmac_f32_e32 v154, v47, v158
	v_fmac_f32_e32 v155, v43, v159
	global_store_dword v160, v140, s[60:61]
	global_store_dword v160, v141, s[60:61] offset:64
	global_store_dword v160, v142, s[60:61] offset:128
	global_store_dword v160, v143, s[60:61] offset:192
	global_store_dword v161, v144, s[60:61]
	global_store_dword v161, v145, s[60:61] offset:64
	global_store_dword v161, v146, s[60:61] offset:128
	global_store_dword v161, v147, s[60:61] offset:192
	global_store_dword v162, v148, s[60:61]
	global_store_dword v162, v149, s[60:61] offset:64
	global_store_dword v162, v150, s[60:61] offset:128
	global_store_dword v162, v151, s[60:61] offset:192
	global_store_dword v163, v152, s[60:61]
	global_store_dword v163, v153, s[60:61] offset:64
	global_store_dword v163, v154, s[60:61] offset:128
	global_store_dword v163, v155, s[60:61] offset:192
	v_add_u32_e32 v164, 160, v101
	v_add_u32_e32 v165, 0xffffe000, v164
	v_lshrrev_b32_e32 v165, 10, v165
	v_add_u32_e32 v165, 1, v165
	v_cmp_lt_i32_e32 vcc, 0x1fff, v164
	s_nop 1
	v_cndmask_b32_e32 v165, 0, v165, vcc
	v_add_u32_e32 v165, s22, v165
	v_mul_u32_u24_e32 v165, 0x6000, v165
	v_add_u32_e32 v166, v165, v100
	v_add_u32_e32 v166, 0xe285000, v166
	global_load_dword v156, v166, s[62:63]
	global_load_dword v157, v166, s[62:63] offset:64
	global_load_dword v158, v166, s[62:63] offset:128
	global_load_dword v159, v166, s[62:63] offset:192
	v_lshl_add_u32 v160, v164, 12, v100
	v_add_u32_e32 v161, 0x1000, v160
	v_add_u32_e32 v162, 0x2000, v160
	v_add_u32_e32 v163, 0x3000, v160
	global_load_dword v140, v160, s[60:61]
	global_load_dword v141, v160, s[60:61] offset:64
	global_load_dword v142, v160, s[60:61] offset:128
	global_load_dword v143, v160, s[60:61] offset:192
	global_load_dword v144, v161, s[60:61]
	global_load_dword v145, v161, s[60:61] offset:64
	global_load_dword v146, v161, s[60:61] offset:128
	global_load_dword v147, v161, s[60:61] offset:192
	global_load_dword v148, v162, s[60:61]
	global_load_dword v149, v162, s[60:61] offset:64
	global_load_dword v150, v162, s[60:61] offset:128
	global_load_dword v151, v162, s[60:61] offset:192
	global_load_dword v152, v163, s[60:61]
	global_load_dword v153, v163, s[60:61] offset:64
	global_load_dword v154, v163, s[60:61] offset:128
	global_load_dword v155, v163, s[60:61] offset:192
	s_waitcnt vmcnt(36)
	v_add_f32_e32 v126, v126, v104
	v_add_f32_e32 v127, v127, v105
	v_add_f32_e32 v128, v128, v106
	v_add_f32_e32 v129, v129, v107
	v_fmac_f32_e32 v110, v36, v126
	v_fmac_f32_e32 v111, v32, v127
	v_fmac_f32_e32 v112, v28, v128
	v_fmac_f32_e32 v113, v24, v129
	v_fmac_f32_e32 v114, v37, v126
	v_fmac_f32_e32 v115, v33, v127
	v_fmac_f32_e32 v116, v29, v128
	v_fmac_f32_e32 v117, v25, v129
	v_fmac_f32_e32 v118, v38, v126
	v_fmac_f32_e32 v119, v34, v127
	v_fmac_f32_e32 v120, v30, v128
	v_fmac_f32_e32 v121, v26, v129
	v_fmac_f32_e32 v122, v39, v126
	v_fmac_f32_e32 v123, v35, v127
	v_fmac_f32_e32 v124, v31, v128
	v_fmac_f32_e32 v125, v27, v129
	global_store_dword v136, v110, s[60:61]
	global_store_dword v136, v111, s[60:61] offset:64
	global_store_dword v136, v112, s[60:61] offset:128
	global_store_dword v136, v113, s[60:61] offset:192
	global_store_dword v137, v114, s[60:61]
	global_store_dword v137, v115, s[60:61] offset:64
	global_store_dword v137, v116, s[60:61] offset:128
	global_store_dword v137, v117, s[60:61] offset:192
	global_store_dword v138, v118, s[60:61]
	global_store_dword v138, v119, s[60:61] offset:64
	global_store_dword v138, v120, s[60:61] offset:128
	global_store_dword v138, v121, s[60:61] offset:192
	global_store_dword v139, v122, s[60:61]
	global_store_dword v139, v123, s[60:61] offset:64
	global_store_dword v139, v124, s[60:61] offset:128
	global_store_dword v139, v125, s[60:61] offset:192
	s_waitcnt vmcnt(16)
	v_add_f32_e32 v156, v156, v104
	v_add_f32_e32 v157, v157, v105
	v_add_f32_e32 v158, v158, v106
	v_add_f32_e32 v159, v159, v107
	v_fmac_f32_e32 v140, v20, v156
	v_fmac_f32_e32 v141, v16, v157
	v_fmac_f32_e32 v142, v12, v158
	v_fmac_f32_e32 v143, v8, v159
	v_fmac_f32_e32 v144, v21, v156
	v_fmac_f32_e32 v145, v17, v157
	v_fmac_f32_e32 v146, v13, v158
	v_fmac_f32_e32 v147, v9, v159
	v_fmac_f32_e32 v148, v22, v156
	v_fmac_f32_e32 v149, v18, v157
	v_fmac_f32_e32 v150, v14, v158
	v_fmac_f32_e32 v151, v10, v159
	v_fmac_f32_e32 v152, v23, v156
	v_fmac_f32_e32 v153, v19, v157
	v_fmac_f32_e32 v154, v15, v158
	v_fmac_f32_e32 v155, v11, v159
	global_store_dword v160, v140, s[60:61]
	global_store_dword v160, v141, s[60:61] offset:64
	global_store_dword v160, v142, s[60:61] offset:128
	global_store_dword v160, v143, s[60:61] offset:192
	global_store_dword v161, v144, s[60:61]
	global_store_dword v161, v145, s[60:61] offset:64
	global_store_dword v161, v146, s[60:61] offset:128
	global_store_dword v161, v147, s[60:61] offset:192
	global_store_dword v162, v148, s[60:61]
	global_store_dword v162, v149, s[60:61] offset:64
	global_store_dword v162, v150, s[60:61] offset:128
	global_store_dword v162, v151, s[60:61] offset:192
	global_store_dword v163, v152, s[60:61]
	global_store_dword v163, v153, s[60:61] offset:64
	global_store_dword v163, v154, s[60:61] offset:128
	global_store_dword v163, v155, s[60:61] offset:192
	v_readlane_b32 s6, v253, 1
	s_nop 3
	s_add_i32 s18, s18, s6
	s_add_i32 s4, s4, s6
	s_cmpk_lt_i32 s18, 0x200
	v_readlane_b32 s7, v253, 2
	s_cbranch_scc0 .LBB0_723

.LBB0_752:
	s_waitcnt vmcnt(0)
	s_mulk_i32 s3, 0xc0
	v_readlane_b32 s44, v253, 53
	v_readlane_b32 s45, v253, 50
	v_and_b32_e32 v132, 0x4f, v196
	v_lshlrev_b32_e32 v132, 2, v132
	v_lshl_or_b32 v132, s2, 9, v132
	v_lshrrev_b32_e32 v133, 3, v196
	v_and_b32_e32 v133, -16, v133
	v_lshrrev_b32_e32 v134, 2, v196
	v_and_b32_e32 v134, 12, v134
	v_add3_u32 v133, v133, v134, s3
	s_lshl_b32 s45, s45, 2
	s_add_i32 s45, s45, 8192
	v_add_u32_e32 v135, s45, v132
	global_load_dword v104, v135, s[78:79]
	global_load_dword v105, v135, s[78:79] offset:64
	global_load_dword v106, v135, s[78:79] offset:128
	global_load_dword v107, v135, s[78:79] offset:192
	v_readlane_b32 s8, v255, 10
	v_readlane_b32 s9, v255, 11
	s_nop 3
	s_and_b64 vcc, exec, s[8:9]
	s_cbranch_vccz .LepiG_in
	v_add_u32_e32 v164, 0, v133
	v_add_u32_e32 v167, 0xffffe000, v164
	v_lshrrev_b32_e32 v165, 10, v167
	v_add_u32_e32 v165, 1, v165
	v_cmp_lt_i32_e32 vcc, 0x1fff, v164
	s_nop 1
	v_cndmask_b32_e32 v165, 0, v165, vcc
	v_add_u32_e32 v165, s44, v165
	v_mul_u32_u24_e32 v165, 0x6000, v165
	v_add_u32_e32 v166, v165, v132
	v_add_u32_e32 v166, 0xe282000, v166
	global_load_dword v126, v166, s[62:63]
	global_load_dword v127, v166, s[62:63] offset:64
	global_load_dword v128, v166, s[62:63] offset:128
	global_load_dword v129, v166, s[62:63] offset:192
	v_lshl_add_u32 v136, v164, 12, v132
	v_add_u32_e32 v137, 0x1000, v136
	v_add_u32_e32 v138, 0x2000, v136
	v_add_u32_e32 v139, 0x3000, v136
	global_load_dword v110, v136, s[60:61]
	global_load_dword v111, v136, s[60:61] offset:64
	global_load_dword v112, v136, s[60:61] offset:128
	global_load_dword v113, v136, s[60:61] offset:192
	global_load_dword v114, v137, s[60:61]
	global_load_dword v115, v137, s[60:61] offset:64
	global_load_dword v116, v137, s[60:61] offset:128
	global_load_dword v117, v137, s[60:61] offset:192
	global_load_dword v118, v138, s[60:61]
	global_load_dword v119, v138, s[60:61] offset:64
	global_load_dword v120, v138, s[60:61] offset:128
	global_load_dword v121, v138, s[60:61] offset:192
	global_load_dword v122, v139, s[60:61]
	global_load_dword v123, v139, s[60:61] offset:64
	global_load_dword v124, v139, s[60:61] offset:128
	global_load_dword v125, v139, s[60:61] offset:192
	v_add_u32_e32 v164, 32, v133
	v_add_u32_e32 v167, 0xffffe000, v164
	v_lshrrev_b32_e32 v165, 10, v167
	v_add_u32_e32 v165, 1, v165
	v_cmp_lt_i32_e32 vcc, 0x1fff, v164
	s_nop 1
	v_cndmask_b32_e32 v165, 0, v165, vcc
	v_add_u32_e32 v165, s44, v165
	v_mul_u32_u24_e32 v165, 0x6000, v165
	v_add_u32_e32 v166, v165, v132
	v_add_u32_e32 v166, 0xe282000, v166
	global_load_dword v156, v166, s[62:63]
	global_load_dword v157, v166, s[62:63] offset:64
	global_load_dword v158, v166, s[62:63] offset:128
	global_load_dword v159, v166, s[62:63] offset:192
	v_lshl_add_u32 v160, v164, 12, v132
	v_add_u32_e32 v161, 0x1000, v160
	v_add_u32_e32 v162, 0x2000, v160
	v_add_u32_e32 v163, 0x3000, v160
	global_load_dword v140, v160, s[60:61]
	global_load_dword v141, v160, s[60:61] offset:64
	global_load_dword v142, v160, s[60:61] offset:128
	global_load_dword v143, v160, s[60:61] offset:192
	global_load_dword v144, v161, s[60:61]
	global_load_dword v145, v161, s[60:61] offset:64
	global_load_dword v146, v161, s[60:61] offset:128
	global_load_dword v147, v161, s[60:61] offset:192
	global_load_dword v148, v162, s[60:61]
	global_load_dword v149, v162, s[60:61] offset:64
	global_load_dword v150, v162, s[60:61] offset:128
	global_load_dword v151, v162, s[60:61] offset:192
	global_load_dword v152, v163, s[60:61]
	global_load_dword v153, v163, s[60:61] offset:64
	global_load_dword v154, v163, s[60:61] offset:128
	global_load_dword v155, v163, s[60:61] offset:192
	s_waitcnt vmcnt(20)
	v_add_f32_e32 v126, v126, v104
	v_add_f32_e32 v127, v127, v105
	v_add_f32_e32 v128, v128, v106
	v_add_f32_e32 v129, v129, v107
	v_fmac_f32_e32 v110, v100, v126
	v_fmac_f32_e32 v111, v96, v127
	v_fmac_f32_e32 v112, v92, v128
	v_fmac_f32_e32 v113, v88, v129
	v_fmac_f32_e32 v114, v101, v126
	v_fmac_f32_e32 v115, v97, v127
	v_fmac_f32_e32 v116, v93, v128
	v_fmac_f32_e32 v117, v89, v129
	v_fmac_f32_e32 v118, v102, v126
	v_fmac_f32_e32 v119, v98, v127
	v_fmac_f32_e32 v120, v94, v128
	v_fmac_f32_e32 v121, v90, v129
	v_fmac_f32_e32 v122, v103, v126
	v_fmac_f32_e32 v123, v99, v127
	v_fmac_f32_e32 v124, v95, v128
	v_fmac_f32_e32 v125, v91, v129
	global_store_dword v136, v110, s[60:61]
	global_store_dword v136, v111, s[60:61] offset:64
	global_store_dword v136, v112, s[60:61] offset:128
	global_store_dword v136, v113, s[60:61] offset:192
	global_store_dword v137, v114, s[60:61]
	global_store_dword v137, v115, s[60:61] offset:64
	global_store_dword v137, v116, s[60:61] offset:128
	global_store_dword v137, v117, s[60:61] offset:192
	global_store_dword v138, v118, s[60:61]
	global_store_dword v138, v119, s[60:61] offset:64
	global_store_dword v138, v120, s[60:61] offset:128
	global_store_dword v138, v121, s[60:61] offset:192
	global_store_dword v139, v122, s[60:61]
	global_store_dword v139, v123, s[60:61] offset:64
	global_store_dword v139, v124, s[60:61] offset:128
	global_store_dword v139, v125, s[60:61] offset:192
	v_add_u32_e32 v164, 64, v133
	v_add_u32_e32 v167, 0xffffe000, v164
	v_lshrrev_b32_e32 v165, 10, v167
	v_add_u32_e32 v165, 1, v165
	v_cmp_lt_i32_e32 vcc, 0x1fff, v164
	s_nop 1
	v_cndmask_b32_e32 v165, 0, v165, vcc
	v_add_u32_e32 v165, s44, v165
	v_mul_u32_u24_e32 v165, 0x6000, v165
	v_add_u32_e32 v166, v165, v132
	v_add_u32_e32 v166, 0xe282000, v166
	global_load_dword v126, v166, s[62:63]
	global_load_dword v127, v166, s[62:63] offset:64
	global_load_dword v128, v166, s[62:63] offset:128
	global_load_dword v129, v166, s[62:63] offset:192
	v_lshl_add_u32 v136, v164, 12, v132
	v_add_u32_e32 v137, 0x1000, v136
	v_add_u32_e32 v138, 0x2000, v136
	v_add_u32_e32 v139, 0x3000, v136
	global_load_dword v110, v136, s[60:61]
	global_load_dword v111, v136, s[60:61] offset:64
	global_load_dword v112, v136, s[60:61] offset:128
	global_load_dword v113, v136, s[60:61] offset:192
	global_load_dword v114, v137, s[60:61]
	global_load_dword v115, v137, s[60:61] offset:64
	global_load_dword v116, v137, s[60:61] offset:128
	global_load_dword v117, v137, s[60:61] offset:192
	global_load_dword v118, v138, s[60:61]
	global_load_dword v119, v138, s[60:61] offset:64
	global_load_dword v120, v138, s[60:61] offset:128
	global_load_dword v121, v138, s[60:61] offset:192
	global_load_dword v122, v139, s[60:61]
	global_load_dword v123, v139, s[60:61] offset:64
	global_load_dword v124, v139, s[60:61] offset:128
	global_load_dword v125, v139, s[60:61] offset:192
	s_waitcnt vmcnt(36)
	v_add_f32_e32 v156, v156, v104
	v_add_f32_e32 v157, v157, v105
	v_add_f32_e32 v158, v158, v106
	v_add_f32_e32 v159, v159, v107
	v_fmac_f32_e32 v140, v84, v156
	v_fmac_f32_e32 v141, v80, v157
	v_fmac_f32_e32 v142, v76, v158
	v_fmac_f32_e32 v143, v72, v159
	v_fmac_f32_e32 v144, v85, v156
	v_fmac_f32_e32 v145, v81, v157
	v_fmac_f32_e32 v146, v77, v158
	v_fmac_f32_e32 v147, v73, v159
	v_fmac_f32_e32 v148, v86, v156
	v_fmac_f32_e32 v149, v82, v157
	v_fmac_f32_e32 v150, v78, v158
	v_fmac_f32_e32 v151, v74, v159
	v_fmac_f32_e32 v152, v87, v156
	v_fmac_f32_e32 v153, v83, v157
	v_fmac_f32_e32 v154, v79, v158
	v_fmac_f32_e32 v155, v75, v159
	global_store_dword v160, v140, s[60:61]
	global_store_dword v160, v141, s[60:61] offset:64
	global_store_dword v160, v142, s[60:61] offset:128
	global_store_dword v160, v143, s[60:61] offset:192
	global_store_dword v161, v144, s[60:61]
	global_store_dword v161, v145, s[60:61] offset:64
	global_store_dword v161, v146, s[60:61] offset:128
	global_store_dword v161, v147, s[60:61] offset:192
	global_store_dword v162, v148, s[60:61]
	global_store_dword v162, v149, s[60:61] offset:64
	global_store_dword v162, v150, s[60:61] offset:128
	global_store_dword v162, v151, s[60:61] offset:192
	global_store_dword v163, v152, s[60:61]
	global_store_dword v163, v153, s[60:61] offset:64
	global_store_dword v163, v154, s[60:61] offset:128
	global_store_dword v163, v155, s[60:61] offset:192
	v_add_u32_e32 v164, 96, v133
	v_add_u32_e32 v167, 0xffffe000, v164
	v_lshrrev_b32_e32 v165, 10, v167
	v_add_u32_e32 v165, 1, v165
	v_cmp_lt_i32_e32 vcc, 0x1fff, v164
	s_nop 1
	v_cndmask_b32_e32 v165, 0, v165, vcc
	v_add_u32_e32 v165, s44, v165
	v_mul_u32_u24_e32 v165, 0x6000, v165
	v_add_u32_e32 v166, v165, v132
	v_add_u32_e32 v166, 0xe282000, v166
	global_load_dword v156, v166, s[62:63]
	global_load_dword v157, v166, s[62:63] offset:64
	global_load_dword v158, v166, s[62:63] offset:128
	global_load_dword v159, v166, s[62:63] offset:192
	v_lshl_add_u32 v160, v164, 12, v132
	v_add_u32_e32 v161, 0x1000, v160
	v_add_u32_e32 v162, 0x2000, v160
	v_add_u32_e32 v163, 0x3000, v160
	global_load_dword v140, v160, s[60:61]
	global_load_dword v141, v160, s[60:61] offset:64
	global_load_dword v142, v160, s[60:61] offset:128
	global_load_dword v143, v160, s[60:61] offset:192
	global_load_dword v144, v161, s[60:61]
	global_load_dword v145, v161, s[60:61] offset:64
	global_load_dword v146, v161, s[60:61] offset:128
	global_load_dword v147, v161, s[60:61] offset:192
	global_load_dword v148, v162, s[60:61]
	global_load_dword v149, v162, s[60:61] offset:64
	global_load_dword v150, v162, s[60:61] offset:128
	global_load_dword v151, v162, s[60:61] offset:192
	global_load_dword v152, v163, s[60:61]
	global_load_dword v153, v163, s[60:61] offset:64
	global_load_dword v154, v163, s[60:61] offset:128
	global_load_dword v155, v163, s[60:61] offset:192
	s_waitcnt vmcnt(36)
	v_add_f32_e32 v126, v126, v104
	v_add_f32_e32 v127, v127, v105
	v_add_f32_e32 v128, v128, v106
	v_add_f32_e32 v129, v129, v107
	v_fmac_f32_e32 v110, v68, v126
	v_fmac_f32_e32 v111, v64, v127
	v_fmac_f32_e32 v112, v60, v128
	v_fmac_f32_e32 v113, v56, v129
	v_fmac_f32_e32 v114, v69, v126
	v_fmac_f32_e32 v115, v65, v127
	v_fmac_f32_e32 v116, v61, v128
	v_fmac_f32_e32 v117, v57, v129
	v_fmac_f32_e32 v118, v70, v126
	v_fmac_f32_e32 v119, v66, v127
	v_fmac_f32_e32 v120, v62, v128
	v_fmac_f32_e32 v121, v58, v129
	v_fmac_f32_e32 v122, v71, v126
	v_fmac_f32_e32 v123, v67, v127
	v_fmac_f32_e32 v124, v63, v128
	v_fmac_f32_e32 v125, v59, v129
	global_store_dword v136, v110, s[60:61]
	global_store_dword v136, v111, s[60:61] offset:64
	global_store_dword v136, v112, s[60:61] offset:128
	global_store_dword v136, v113, s[60:61] offset:192
	global_store_dword v137, v114, s[60:61]
	global_store_dword v137, v115, s[60:61] offset:64
	global_store_dword v137, v116, s[60:61] offset:128
	global_store_dword v137, v117, s[60:61] offset:192
	global_store_dword v138, v118, s[60:61]
	global_store_dword v138, v119, s[60:61] offset:64
	global_store_dword v138, v120, s[60:61] offset:128
	global_store_dword v138, v121, s[60:61] offset:192
	global_store_dword v139, v122, s[60:61]
	global_store_dword v139, v123, s[60:61] offset:64
	global_store_dword v139, v124, s[60:61] offset:128
	global_store_dword v139, v125, s[60:61] offset:192
	v_add_u32_e32 v164, 128, v133
	v_add_u32_e32 v167, 0xffffe000, v164
	v_lshrrev_b32_e32 v165, 10, v167
	v_add_u32_e32 v165, 1, v165
	v_cmp_lt_i32_e32 vcc, 0x1fff, v164
	s_nop 1
	v_cndmask_b32_e32 v165, 0, v165, vcc
	v_add_u32_e32 v165, s44, v165
	v_mul_u32_u24_e32 v165, 0x6000, v165
	v_add_u32_e32 v166, v165, v132
	v_add_u32_e32 v166, 0xe282000, v166
	global_load_dword v126, v166, s[62:63]
	global_load_dword v127, v166, s[62:63] offset:64
	global_load_dword v128, v166, s[62:63] offset:128
	global_load_dword v129, v166, s[62:63] offset:192
	v_lshl_add_u32 v136, v164, 12, v132
	v_add_u32_e32 v137, 0x1000, v136
	v_add_u32_e32 v138, 0x2000, v136
	v_add_u32_e32 v139, 0x3000, v136
	global_load_dword v110, v136, s[60:61]
	global_load_dword v111, v136, s[60:61] offset:64
	global_load_dword v112, v136, s[60:61] offset:128
	global_load_dword v113, v136, s[60:61] offset:192
	global_load_dword v114, v137, s[60:61]
	global_load_dword v115, v137, s[60:61] offset:64
	global_load_dword v116, v137, s[60:61] offset:128
	global_load_dword v117, v137, s[60:61] offset:192
	global_load_dword v118, v138, s[60:61]
	global_load_dword v119, v138, s[60:61] offset:64
	global_load_dword v120, v138, s[60:61] offset:128
	global_load_dword v121, v138, s[60:61] offset:192
	global_load_dword v122, v139, s[60:61]
	global_load_dword v123, v139, s[60:61] offset:64
	global_load_dword v124, v139, s[60:61] offset:128
	global_load_dword v125, v139, s[60:61] offset:192
	s_waitcnt vmcnt(36)
	v_add_f32_e32 v156, v156, v104
	v_add_f32_e32 v157, v157, v105
	v_add_f32_e32 v158, v158, v106
	v_add_f32_e32 v159, v159, v107
	v_fmac_f32_e32 v140, v52, v156
	v_fmac_f32_e32 v141, v48, v157
	v_fmac_f32_e32 v142, v44, v158
	v_fmac_f32_e32 v143, v40, v159
	v_fmac_f32_e32 v144, v53, v156
	v_fmac_f32_e32 v145, v49, v157
	v_fmac_f32_e32 v146, v45, v158
	v_fmac_f32_e32 v147, v41, v159
	v_fmac_f32_e32 v148, v54, v156
	v_fmac_f32_e32 v149, v50, v157
	v_fmac_f32_e32 v150, v46, v158
	v_fmac_f32_e32 v151, v42, v159
	v_fmac_f32_e32 v152, v55, v156
	v_fmac_f32_e32 v153, v51, v157
	v_fmac_f32_e32 v154, v47, v158
	v_fmac_f32_e32 v155, v43, v159
	global_store_dword v160, v140, s[60:61]
	global_store_dword v160, v141, s[60:61] offset:64
	global_store_dword v160, v142, s[60:61] offset:128
	global_store_dword v160, v143, s[60:61] offset:192
	global_store_dword v161, v144, s[60:61]
	global_store_dword v161, v145, s[60:61] offset:64
	global_store_dword v161, v146, s[60:61] offset:128
	global_store_dword v161, v147, s[60:61] offset:192
	global_store_dword v162, v148, s[60:61]
	global_store_dword v162, v149, s[60:61] offset:64
	global_store_dword v162, v150, s[60:61] offset:128
	global_store_dword v162, v151, s[60:61] offset:192
	global_store_dword v163, v152, s[60:61]
	global_store_dword v163, v153, s[60:61] offset:64
	global_store_dword v163, v154, s[60:61] offset:128
	global_store_dword v163, v155, s[60:61] offset:192
	v_add_u32_e32 v164, 160, v133
	v_add_u32_e32 v167, 0xffffe000, v164
	v_lshrrev_b32_e32 v165, 10, v167
	v_add_u32_e32 v165, 1, v165
	v_cmp_lt_i32_e32 vcc, 0x1fff, v164
	s_nop 1
	v_cndmask_b32_e32 v165, 0, v165, vcc
	v_add_u32_e32 v165, s44, v165
	v_mul_u32_u24_e32 v165, 0x6000, v165
	v_add_u32_e32 v166, v165, v132
	v_add_u32_e32 v166, 0xe282000, v166
	global_load_dword v156, v166, s[62:63]
	global_load_dword v157, v166, s[62:63] offset:64
	global_load_dword v158, v166, s[62:63] offset:128
	global_load_dword v159, v166, s[62:63] offset:192
	v_lshl_add_u32 v160, v164, 12, v132
	v_add_u32_e32 v161, 0x1000, v160
	v_add_u32_e32 v162, 0x2000, v160
	v_add_u32_e32 v163, 0x3000, v160
	global_load_dword v140, v160, s[60:61]
	global_load_dword v141, v160, s[60:61] offset:64
	global_load_dword v142, v160, s[60:61] offset:128
	global_load_dword v143, v160, s[60:61] offset:192
	global_load_dword v144, v161, s[60:61]
	global_load_dword v145, v161, s[60:61] offset:64
	global_load_dword v146, v161, s[60:61] offset:128
	global_load_dword v147, v161, s[60:61] offset:192
	global_load_dword v148, v162, s[60:61]
	global_load_dword v149, v162, s[60:61] offset:64
	global_load_dword v150, v162, s[60:61] offset:128
	global_load_dword v151, v162, s[60:61] offset:192
	global_load_dword v152, v163, s[60:61]
	global_load_dword v153, v163, s[60:61] offset:64
	global_load_dword v154, v163, s[60:61] offset:128
	global_load_dword v155, v163, s[60:61] offset:192
	s_waitcnt vmcnt(36)
	v_add_f32_e32 v126, v126, v104
	v_add_f32_e32 v127, v127, v105
	v_add_f32_e32 v128, v128, v106
	v_add_f32_e32 v129, v129, v107
	v_fmac_f32_e32 v110, v36, v126
	v_fmac_f32_e32 v111, v32, v127
	v_fmac_f32_e32 v112, v28, v128
	v_fmac_f32_e32 v113, v24, v129
	v_fmac_f32_e32 v114, v37, v126
	v_fmac_f32_e32 v115, v33, v127
	v_fmac_f32_e32 v116, v29, v128
	v_fmac_f32_e32 v117, v25, v129
	v_fmac_f32_e32 v118, v38, v126
	v_fmac_f32_e32 v119, v34, v127
	v_fmac_f32_e32 v120, v30, v128
	v_fmac_f32_e32 v121, v26, v129
	v_fmac_f32_e32 v122, v39, v126
	v_fmac_f32_e32 v123, v35, v127
	v_fmac_f32_e32 v124, v31, v128
	v_fmac_f32_e32 v125, v27, v129
	global_store_dword v136, v110, s[60:61]
	global_store_dword v136, v111, s[60:61] offset:64
	global_store_dword v136, v112, s[60:61] offset:128
	global_store_dword v136, v113, s[60:61] offset:192
	global_store_dword v137, v114, s[60:61]
	global_store_dword v137, v115, s[60:61] offset:64
	global_store_dword v137, v116, s[60:61] offset:128
	global_store_dword v137, v117, s[60:61] offset:192
	global_store_dword v138, v118, s[60:61]
	global_store_dword v138, v119, s[60:61] offset:64
	global_store_dword v138, v120, s[60:61] offset:128
	global_store_dword v138, v121, s[60:61] offset:192
	global_store_dword v139, v122, s[60:61]
	global_store_dword v139, v123, s[60:61] offset:64
	global_store_dword v139, v124, s[60:61] offset:128
	global_store_dword v139, v125, s[60:61] offset:192
	s_waitcnt vmcnt(16)
	v_add_f32_e32 v156, v156, v104
	v_add_f32_e32 v157, v157, v105
	v_add_f32_e32 v158, v158, v106
	v_add_f32_e32 v159, v159, v107
	v_fmac_f32_e32 v140, v20, v156
	v_fmac_f32_e32 v141, v16, v157
	v_fmac_f32_e32 v142, v12, v158
	v_fmac_f32_e32 v143, v8, v159
	v_fmac_f32_e32 v144, v21, v156
	v_fmac_f32_e32 v145, v17, v157
	v_fmac_f32_e32 v146, v13, v158
	v_fmac_f32_e32 v147, v9, v159
	v_fmac_f32_e32 v148, v22, v156
	v_fmac_f32_e32 v149, v18, v157
	v_fmac_f32_e32 v150, v14, v158
	v_fmac_f32_e32 v151, v10, v159
	v_fmac_f32_e32 v152, v23, v156
	v_fmac_f32_e32 v153, v19, v157
	v_fmac_f32_e32 v154, v15, v158
	v_fmac_f32_e32 v155, v11, v159
	global_store_dword v160, v140, s[60:61]
	global_store_dword v160, v141, s[60:61] offset:64
	global_store_dword v160, v142, s[60:61] offset:128
	global_store_dword v160, v143, s[60:61] offset:192
	global_store_dword v161, v144, s[60:61]
	global_store_dword v161, v145, s[60:61] offset:64
	global_store_dword v161, v146, s[60:61] offset:128
	global_store_dword v161, v147, s[60:61] offset:192
	global_store_dword v162, v148, s[60:61]
	global_store_dword v162, v149, s[60:61] offset:64
	global_store_dword v162, v150, s[60:61] offset:128
	global_store_dword v162, v151, s[60:61] offset:192
	global_store_dword v163, v152, s[60:61]
	global_store_dword v163, v153, s[60:61] offset:64
	global_store_dword v163, v154, s[60:61] offset:128
	global_store_dword v163, v155, s[60:61] offset:192
	v_readlane_b32 s20, v253, 55
	v_readlane_b32 s21, v253, 56
	v_readlane_b32 s0, v253, 1
	s_nop 3
	s_add_i32 s16, s16, s0
	s_add_i32 s4, s4, s0
	s_cmpk_gt_i32 s16, 0x1ff
	v_readlane_b32 s1, v253, 2
	s_cbranch_scc1 .LBB0_1519
	s_branch .LBB0_748
.LepiG_in:
	v_add_u32_e32 v164, 0, v133
	v_add_u32_e32 v167, 0xffffe000, v164
	v_lshrrev_b32_e32 v165, 10, v167
	v_add_u32_e32 v165, 1, v165
	v_cmp_lt_i32_e32 vcc, 0x1fff, v164
	s_nop 1
	v_cndmask_b32_e32 v165, 0, v165, vcc
	v_cndmask_b32_e32 v167, v164, v167, vcc
	v_mov_b32_e32 v184, s64
	v_mov_b32_e32 v131, s65
	v_mov_b32_e32 v166, s66
	v_cndmask_b32_e32 v184, v184, v166, vcc
	v_mov_b32_e32 v166, s67
	v_cndmask_b32_e32 v131, v131, v166, vcc
	v_add_u32_e32 v165, s44, v165
	v_mul_u32_u24_e32 v165, 0x6000, v165
	v_add_u32_e32 v166, v165, v132
	v_add_u32_e32 v166, 0xe282000, v166
	global_load_dword v126, v166, s[62:63]
	global_load_dword v127, v166, s[62:63] offset:64
	global_load_dword v128, v166, s[62:63] offset:128
	global_load_dword v129, v166, s[62:63] offset:192
	v_lshl_add_u32 v136, v164, 12, v132
	v_add_u32_e32 v137, 0x1000, v136
	v_add_u32_e32 v138, 0x2000, v136
	v_add_u32_e32 v139, 0x3000, v136
	v_lshl_add_u32 v166, v167, 12, v132
	v_add_co_u32_e32 v168, vcc, v184, v166
	s_nop 1
	v_addc_co_u32_e32 v169, vcc, 0, v131, vcc
	s_mov_b64 s[98:99], 0x1000
	v_lshl_add_u64 v[170:171], v[168:169], 0, s[98:99]
	v_lshl_add_u64 v[172:173], v[170:171], 0, s[98:99]
	v_lshl_add_u64 v[174:175], v[172:173], 0, s[98:99]
	global_load_dword v110, v[168:169], off
	global_load_dword v111, v[168:169], off offset:64
	global_load_dword v112, v[168:169], off offset:128
	global_load_dword v113, v[168:169], off offset:192
	global_load_dword v114, v[170:171], off
	global_load_dword v115, v[170:171], off offset:64
	global_load_dword v116, v[170:171], off offset:128
	global_load_dword v117, v[170:171], off offset:192
	global_load_dword v118, v[172:173], off
	global_load_dword v119, v[172:173], off offset:64
	global_load_dword v120, v[172:173], off offset:128
	global_load_dword v121, v[172:173], off offset:192
	global_load_dword v122, v[174:175], off
	global_load_dword v123, v[174:175], off offset:64
	global_load_dword v124, v[174:175], off offset:128
	global_load_dword v125, v[174:175], off offset:192
	v_add_u32_e32 v164, 32, v133
	v_add_u32_e32 v167, 0xffffe000, v164
	v_lshrrev_b32_e32 v165, 10, v167
	v_add_u32_e32 v165, 1, v165
	v_cmp_lt_i32_e32 vcc, 0x1fff, v164
	s_nop 1
	v_cndmask_b32_e32 v165, 0, v165, vcc
	v_cndmask_b32_e32 v167, v164, v167, vcc
	v_mov_b32_e32 v184, s64
	v_mov_b32_e32 v131, s65
	v_mov_b32_e32 v166, s66
	v_cndmask_b32_e32 v184, v184, v166, vcc
	v_mov_b32_e32 v166, s67
	v_cndmask_b32_e32 v131, v131, v166, vcc
	v_add_u32_e32 v165, s44, v165
	v_mul_u32_u24_e32 v165, 0x6000, v165
	v_add_u32_e32 v166, v165, v132
	v_add_u32_e32 v166, 0xe282000, v166
	global_load_dword v156, v166, s[62:63]
	global_load_dword v157, v166, s[62:63] offset:64
	global_load_dword v158, v166, s[62:63] offset:128
	global_load_dword v159, v166, s[62:63] offset:192
	v_lshl_add_u32 v160, v164, 12, v132
	v_add_u32_e32 v161, 0x1000, v160
	v_add_u32_e32 v162, 0x2000, v160
	v_add_u32_e32 v163, 0x3000, v160
	v_lshl_add_u32 v166, v167, 12, v132
	v_add_co_u32_e32 v176, vcc, v184, v166
	s_nop 1
	v_addc_co_u32_e32 v177, vcc, 0, v131, vcc
	s_mov_b64 s[98:99], 0x1000
	v_lshl_add_u64 v[178:179], v[176:177], 0, s[98:99]
	v_lshl_add_u64 v[180:181], v[178:179], 0, s[98:99]
	v_lshl_add_u64 v[182:183], v[180:181], 0, s[98:99]
	global_load_dword v140, v[176:177], off
	global_load_dword v141, v[176:177], off offset:64
	global_load_dword v142, v[176:177], off offset:128
	global_load_dword v143, v[176:177], off offset:192
	global_load_dword v144, v[178:179], off
	global_load_dword v145, v[178:179], off offset:64
	global_load_dword v146, v[178:179], off offset:128
	global_load_dword v147, v[178:179], off offset:192
	global_load_dword v148, v[180:181], off
	global_load_dword v149, v[180:181], off offset:64
	global_load_dword v150, v[180:181], off offset:128
	global_load_dword v151, v[180:181], off offset:192
	global_load_dword v152, v[182:183], off
	global_load_dword v153, v[182:183], off offset:64
	global_load_dword v154, v[182:183], off offset:128
	global_load_dword v155, v[182:183], off offset:192
	s_waitcnt vmcnt(20)
	v_add_f32_e32 v126, v126, v104
	v_add_f32_e32 v127, v127, v105
	v_add_f32_e32 v128, v128, v106
	v_add_f32_e32 v129, v129, v107
	v_fmac_f32_e32 v110, v100, v126
	v_fmac_f32_e32 v111, v96, v127
	v_fmac_f32_e32 v112, v92, v128
	v_fmac_f32_e32 v113, v88, v129
	v_fmac_f32_e32 v114, v101, v126
	v_fmac_f32_e32 v115, v97, v127
	v_fmac_f32_e32 v116, v93, v128
	v_fmac_f32_e32 v117, v89, v129
	v_fmac_f32_e32 v118, v102, v126
	v_fmac_f32_e32 v119, v98, v127
	v_fmac_f32_e32 v120, v94, v128
	v_fmac_f32_e32 v121, v90, v129
	v_fmac_f32_e32 v122, v103, v126
	v_fmac_f32_e32 v123, v99, v127
	v_fmac_f32_e32 v124, v95, v128
	v_fmac_f32_e32 v125, v91, v129
	global_store_dword v136, v110, s[60:61]
	global_store_dword v136, v111, s[60:61] offset:64
	global_store_dword v136, v112, s[60:61] offset:128
	global_store_dword v136, v113, s[60:61] offset:192
	global_store_dword v137, v114, s[60:61]
	global_store_dword v137, v115, s[60:61] offset:64
	global_store_dword v137, v116, s[60:61] offset:128
	global_store_dword v137, v117, s[60:61] offset:192
	global_store_dword v138, v118, s[60:61]
	global_store_dword v138, v119, s[60:61] offset:64
	global_store_dword v138, v120, s[60:61] offset:128
	global_store_dword v138, v121, s[60:61] offset:192
	global_store_dword v139, v122, s[60:61]
	global_store_dword v139, v123, s[60:61] offset:64
	global_store_dword v139, v124, s[60:61] offset:128
	global_store_dword v139, v125, s[60:61] offset:192
	v_add_u32_e32 v164, 64, v133
	v_add_u32_e32 v167, 0xffffe000, v164
	v_lshrrev_b32_e32 v165, 10, v167
	v_add_u32_e32 v165, 1, v165
	v_cmp_lt_i32_e32 vcc, 0x1fff, v164
	s_nop 1
	v_cndmask_b32_e32 v165, 0, v165, vcc
	v_cndmask_b32_e32 v167, v164, v167, vcc
	v_mov_b32_e32 v184, s64
	v_mov_b32_e32 v131, s65
	v_mov_b32_e32 v166, s66
	v_cndmask_b32_e32 v184, v184, v166, vcc
	v_mov_b32_e32 v166, s67
	v_cndmask_b32_e32 v131, v131, v166, vcc
	v_add_u32_e32 v165, s44, v165
	v_mul_u32_u24_e32 v165, 0x6000, v165
	v_add_u32_e32 v166, v165, v132
	v_add_u32_e32 v166, 0xe282000, v166
	global_load_dword v126, v166, s[62:63]
	global_load_dword v127, v166, s[62:63] offset:64
	global_load_dword v128, v166, s[62:63] offset:128
	global_load_dword v129, v166, s[62:63] offset:192
	v_lshl_add_u32 v136, v164, 12, v132
	v_add_u32_e32 v137, 0x1000, v136
	v_add_u32_e32 v138, 0x2000, v136
	v_add_u32_e32 v139, 0x3000, v136
	v_lshl_add_u32 v166, v167, 12, v132
	v_add_co_u32_e32 v168, vcc, v184, v166
	s_nop 1
	v_addc_co_u32_e32 v169, vcc, 0, v131, vcc
	s_mov_b64 s[98:99], 0x1000
	v_lshl_add_u64 v[170:171], v[168:169], 0, s[98:99]
	v_lshl_add_u64 v[172:173], v[170:171], 0, s[98:99]
	v_lshl_add_u64 v[174:175], v[172:173], 0, s[98:99]
	global_load_dword v110, v[168:169], off
	global_load_dword v111, v[168:169], off offset:64
	global_load_dword v112, v[168:169], off offset:128
	global_load_dword v113, v[168:169], off offset:192
	global_load_dword v114, v[170:171], off
	global_load_dword v115, v[170:171], off offset:64
	global_load_dword v116, v[170:171], off offset:128
	global_load_dword v117, v[170:171], off offset:192
	global_load_dword v118, v[172:173], off
	global_load_dword v119, v[172:173], off offset:64
	global_load_dword v120, v[172:173], off offset:128
	global_load_dword v121, v[172:173], off offset:192
	global_load_dword v122, v[174:175], off
	global_load_dword v123, v[174:175], off offset:64
	global_load_dword v124, v[174:175], off offset:128
	global_load_dword v125, v[174:175], off offset:192
	s_waitcnt vmcnt(36)
	v_add_f32_e32 v156, v156, v104
	v_add_f32_e32 v157, v157, v105
	v_add_f32_e32 v158, v158, v106
	v_add_f32_e32 v159, v159, v107
	v_fmac_f32_e32 v140, v84, v156
	v_fmac_f32_e32 v141, v80, v157
	v_fmac_f32_e32 v142, v76, v158
	v_fmac_f32_e32 v143, v72, v159
	v_fmac_f32_e32 v144, v85, v156
	v_fmac_f32_e32 v145, v81, v157
	v_fmac_f32_e32 v146, v77, v158
	v_fmac_f32_e32 v147, v73, v159
	v_fmac_f32_e32 v148, v86, v156
	v_fmac_f32_e32 v149, v82, v157
	v_fmac_f32_e32 v150, v78, v158
	v_fmac_f32_e32 v151, v74, v159
	v_fmac_f32_e32 v152, v87, v156
	v_fmac_f32_e32 v153, v83, v157
	v_fmac_f32_e32 v154, v79, v158
	v_fmac_f32_e32 v155, v75, v159
	global_store_dword v160, v140, s[60:61]
	global_store_dword v160, v141, s[60:61] offset:64
	global_store_dword v160, v142, s[60:61] offset:128
	global_store_dword v160, v143, s[60:61] offset:192
	global_store_dword v161, v144, s[60:61]
	global_store_dword v161, v145, s[60:61] offset:64
	global_store_dword v161, v146, s[60:61] offset:128
	global_store_dword v161, v147, s[60:61] offset:192
	global_store_dword v162, v148, s[60:61]
	global_store_dword v162, v149, s[60:61] offset:64
	global_store_dword v162, v150, s[60:61] offset:128
	global_store_dword v162, v151, s[60:61] offset:192
	global_store_dword v163, v152, s[60:61]
	global_store_dword v163, v153, s[60:61] offset:64
	global_store_dword v163, v154, s[60:61] offset:128
	global_store_dword v163, v155, s[60:61] offset:192
	v_add_u32_e32 v164, 96, v133
	v_add_u32_e32 v167, 0xffffe000, v164
	v_lshrrev_b32_e32 v165, 10, v167
	v_add_u32_e32 v165, 1, v165
	v_cmp_lt_i32_e32 vcc, 0x1fff, v164
	s_nop 1
	v_cndmask_b32_e32 v165, 0, v165, vcc
	v_cndmask_b32_e32 v167, v164, v167, vcc
	v_mov_b32_e32 v184, s64
	v_mov_b32_e32 v131, s65
	v_mov_b32_e32 v166, s66
	v_cndmask_b32_e32 v184, v184, v166, vcc
	v_mov_b32_e32 v166, s67
	v_cndmask_b32_e32 v131, v131, v166, vcc
	v_add_u32_e32 v165, s44, v165
	v_mul_u32_u24_e32 v165, 0x6000, v165
	v_add_u32_e32 v166, v165, v132
	v_add_u32_e32 v166, 0xe282000, v166
	global_load_dword v156, v166, s[62:63]
	global_load_dword v157, v166, s[62:63] offset:64
	global_load_dword v158, v166, s[62:63] offset:128
	global_load_dword v159, v166, s[62:63] offset:192
	v_lshl_add_u32 v160, v164, 12, v132
	v_add_u32_e32 v161, 0x1000, v160
	v_add_u32_e32 v162, 0x2000, v160
	v_add_u32_e32 v163, 0x3000, v160
	v_lshl_add_u32 v166, v167, 12, v132
	v_add_co_u32_e32 v176, vcc, v184, v166
	s_nop 1
	v_addc_co_u32_e32 v177, vcc, 0, v131, vcc
	s_mov_b64 s[98:99], 0x1000
	v_lshl_add_u64 v[178:179], v[176:177], 0, s[98:99]
	v_lshl_add_u64 v[180:181], v[178:179], 0, s[98:99]
	v_lshl_add_u64 v[182:183], v[180:181], 0, s[98:99]
	global_load_dword v140, v[176:177], off
	global_load_dword v141, v[176:177], off offset:64
	global_load_dword v142, v[176:177], off offset:128
	global_load_dword v143, v[176:177], off offset:192
	global_load_dword v144, v[178:179], off
	global_load_dword v145, v[178:179], off offset:64
	global_load_dword v146, v[178:179], off offset:128
	global_load_dword v147, v[178:179], off offset:192
	global_load_dword v148, v[180:181], off
	global_load_dword v149, v[180:181], off offset:64
	global_load_dword v150, v[180:181], off offset:128
	global_load_dword v151, v[180:181], off offset:192
	global_load_dword v152, v[182:183], off
	global_load_dword v153, v[182:183], off offset:64
	global_load_dword v154, v[182:183], off offset:128
	global_load_dword v155, v[182:183], off offset:192
	s_waitcnt vmcnt(36)
	v_add_f32_e32 v126, v126, v104
	v_add_f32_e32 v127, v127, v105
	v_add_f32_e32 v128, v128, v106
	v_add_f32_e32 v129, v129, v107
	v_fmac_f32_e32 v110, v68, v126
	v_fmac_f32_e32 v111, v64, v127
	v_fmac_f32_e32 v112, v60, v128
	v_fmac_f32_e32 v113, v56, v129
	v_fmac_f32_e32 v114, v69, v126
	v_fmac_f32_e32 v115, v65, v127
	v_fmac_f32_e32 v116, v61, v128
	v_fmac_f32_e32 v117, v57, v129
	v_fmac_f32_e32 v118, v70, v126
	v_fmac_f32_e32 v119, v66, v127
	v_fmac_f32_e32 v120, v62, v128
	v_fmac_f32_e32 v121, v58, v129
	v_fmac_f32_e32 v122, v71, v126
	v_fmac_f32_e32 v123, v67, v127
	v_fmac_f32_e32 v124, v63, v128
	v_fmac_f32_e32 v125, v59, v129
	global_store_dword v136, v110, s[60:61]
	global_store_dword v136, v111, s[60:61] offset:64
	global_store_dword v136, v112, s[60:61] offset:128
	global_store_dword v136, v113, s[60:61] offset:192
	global_store_dword v137, v114, s[60:61]
	global_store_dword v137, v115, s[60:61] offset:64
	global_store_dword v137, v116, s[60:61] offset:128
	global_store_dword v137, v117, s[60:61] offset:192
	global_store_dword v138, v118, s[60:61]
	global_store_dword v138, v119, s[60:61] offset:64
	global_store_dword v138, v120, s[60:61] offset:128
	global_store_dword v138, v121, s[60:61] offset:192
	global_store_dword v139, v122, s[60:61]
	global_store_dword v139, v123, s[60:61] offset:64
	global_store_dword v139, v124, s[60:61] offset:128
	global_store_dword v139, v125, s[60:61] offset:192
	v_add_u32_e32 v164, 128, v133
	v_add_u32_e32 v167, 0xffffe000, v164
	v_lshrrev_b32_e32 v165, 10, v167
	v_add_u32_e32 v165, 1, v165
	v_cmp_lt_i32_e32 vcc, 0x1fff, v164
	s_nop 1
	v_cndmask_b32_e32 v165, 0, v165, vcc
	v_cndmask_b32_e32 v167, v164, v167, vcc
	v_mov_b32_e32 v184, s64
	v_mov_b32_e32 v131, s65
	v_mov_b32_e32 v166, s66
	v_cndmask_b32_e32 v184, v184, v166, vcc
	v_mov_b32_e32 v166, s67
	v_cndmask_b32_e32 v131, v131, v166, vcc
	v_add_u32_e32 v165, s44, v165
	v_mul_u32_u24_e32 v165, 0x6000, v165
	v_add_u32_e32 v166, v165, v132
	v_add_u32_e32 v166, 0xe282000, v166
	global_load_dword v126, v166, s[62:63]
	global_load_dword v127, v166, s[62:63] offset:64
	global_load_dword v128, v166, s[62:63] offset:128
	global_load_dword v129, v166, s[62:63] offset:192
	v_lshl_add_u32 v136, v164, 12, v132
	v_add_u32_e32 v137, 0x1000, v136
	v_add_u32_e32 v138, 0x2000, v136
	v_add_u32_e32 v139, 0x3000, v136
	v_lshl_add_u32 v166, v167, 12, v132
	v_add_co_u32_e32 v168, vcc, v184, v166
	s_nop 1
	v_addc_co_u32_e32 v169, vcc, 0, v131, vcc
	s_mov_b64 s[98:99], 0x1000
	v_lshl_add_u64 v[170:171], v[168:169], 0, s[98:99]
	v_lshl_add_u64 v[172:173], v[170:171], 0, s[98:99]
	v_lshl_add_u64 v[174:175], v[172:173], 0, s[98:99]
	global_load_dword v110, v[168:169], off
	global_load_dword v111, v[168:169], off offset:64
	global_load_dword v112, v[168:169], off offset:128
	global_load_dword v113, v[168:169], off offset:192
	global_load_dword v114, v[170:171], off
	global_load_dword v115, v[170:171], off offset:64
	global_load_dword v116, v[170:171], off offset:128
	global_load_dword v117, v[170:171], off offset:192
	global_load_dword v118, v[172:173], off
	global_load_dword v119, v[172:173], off offset:64
	global_load_dword v120, v[172:173], off offset:128
	global_load_dword v121, v[172:173], off offset:192
	global_load_dword v122, v[174:175], off
	global_load_dword v123, v[174:175], off offset:64
	global_load_dword v124, v[174:175], off offset:128
	global_load_dword v125, v[174:175], off offset:192
	s_waitcnt vmcnt(36)
	v_add_f32_e32 v156, v156, v104
	v_add_f32_e32 v157, v157, v105
	v_add_f32_e32 v158, v158, v106
	v_add_f32_e32 v159, v159, v107
	v_fmac_f32_e32 v140, v52, v156
	v_fmac_f32_e32 v141, v48, v157
	v_fmac_f32_e32 v142, v44, v158
	v_fmac_f32_e32 v143, v40, v159
	v_fmac_f32_e32 v144, v53, v156
	v_fmac_f32_e32 v145, v49, v157
	v_fmac_f32_e32 v146, v45, v158
	v_fmac_f32_e32 v147, v41, v159
	v_fmac_f32_e32 v148, v54, v156
	v_fmac_f32_e32 v149, v50, v157
	v_fmac_f32_e32 v150, v46, v158
	v_fmac_f32_e32 v151, v42, v159
	v_fmac_f32_e32 v152, v55, v156
	v_fmac_f32_e32 v153, v51, v157
	v_fmac_f32_e32 v154, v47, v158
	v_fmac_f32_e32 v155, v43, v159
	global_store_dword v160, v140, s[60:61]
	global_store_dword v160, v141, s[60:61] offset:64
	global_store_dword v160, v142, s[60:61] offset:128
	global_store_dword v160, v143, s[60:61] offset:192
	global_store_dword v161, v144, s[60:61]
	global_store_dword v161, v145, s[60:61] offset:64
	global_store_dword v161, v146, s[60:61] offset:128
	global_store_dword v161, v147, s[60:61] offset:192
	global_store_dword v162, v148, s[60:61]
	global_store_dword v162, v149, s[60:61] offset:64
	global_store_dword v162, v150, s[60:61] offset:128
	global_store_dword v162, v151, s[60:61] offset:192
	global_store_dword v163, v152, s[60:61]
	global_store_dword v163, v153, s[60:61] offset:64
	global_store_dword v163, v154, s[60:61] offset:128
	global_store_dword v163, v155, s[60:61] offset:192
	v_add_u32_e32 v164, 160, v133
	v_add_u32_e32 v167, 0xffffe000, v164
	v_lshrrev_b32_e32 v165, 10, v167
	v_add_u32_e32 v165, 1, v165
	v_cmp_lt_i32_e32 vcc, 0x1fff, v164
	s_nop 1
	v_cndmask_b32_e32 v165, 0, v165, vcc
	v_cndmask_b32_e32 v167, v164, v167, vcc
	v_mov_b32_e32 v184, s64
	v_mov_b32_e32 v131, s65
	v_mov_b32_e32 v166, s66
	v_cndmask_b32_e32 v184, v184, v166, vcc
	v_mov_b32_e32 v166, s67
	v_cndmask_b32_e32 v131, v131, v166, vcc
	v_add_u32_e32 v165, s44, v165
	v_mul_u32_u24_e32 v165, 0x6000, v165
	v_add_u32_e32 v166, v165, v132
	v_add_u32_e32 v166, 0xe282000, v166
	global_load_dword v156, v166, s[62:63]
	global_load_dword v157, v166, s[62:63] offset:64
	global_load_dword v158, v166, s[62:63] offset:128
	global_load_dword v159, v166, s[62:63] offset:192
	v_lshl_add_u32 v160, v164, 12, v132
	v_add_u32_e32 v161, 0x1000, v160
	v_add_u32_e32 v162, 0x2000, v160
	v_add_u32_e32 v163, 0x3000, v160
	v_lshl_add_u32 v166, v167, 12, v132
	v_add_co_u32_e32 v176, vcc, v184, v166
	s_nop 1
	v_addc_co_u32_e32 v177, vcc, 0, v131, vcc
	s_mov_b64 s[98:99], 0x1000
	v_lshl_add_u64 v[178:179], v[176:177], 0, s[98:99]
	v_lshl_add_u64 v[180:181], v[178:179], 0, s[98:99]
	v_lshl_add_u64 v[182:183], v[180:181], 0, s[98:99]
	global_load_dword v140, v[176:177], off
	global_load_dword v141, v[176:177], off offset:64
	global_load_dword v142, v[176:177], off offset:128
	global_load_dword v143, v[176:177], off offset:192
	global_load_dword v144, v[178:179], off
	global_load_dword v145, v[178:179], off offset:64
	global_load_dword v146, v[178:179], off offset:128
	global_load_dword v147, v[178:179], off offset:192
	global_load_dword v148, v[180:181], off
	global_load_dword v149, v[180:181], off offset:64
	global_load_dword v150, v[180:181], off offset:128
	global_load_dword v151, v[180:181], off offset:192
	global_load_dword v152, v[182:183], off
	global_load_dword v153, v[182:183], off offset:64
	global_load_dword v154, v[182:183], off offset:128
	global_load_dword v155, v[182:183], off offset:192
	s_waitcnt vmcnt(36)
	v_add_f32_e32 v126, v126, v104
	v_add_f32_e32 v127, v127, v105
	v_add_f32_e32 v128, v128, v106
	v_add_f32_e32 v129, v129, v107
	v_fmac_f32_e32 v110, v36, v126
	v_fmac_f32_e32 v111, v32, v127
	v_fmac_f32_e32 v112, v28, v128
	v_fmac_f32_e32 v113, v24, v129
	v_fmac_f32_e32 v114, v37, v126
	v_fmac_f32_e32 v115, v33, v127
	v_fmac_f32_e32 v116, v29, v128
	v_fmac_f32_e32 v117, v25, v129
	v_fmac_f32_e32 v118, v38, v126
	v_fmac_f32_e32 v119, v34, v127
	v_fmac_f32_e32 v120, v30, v128
	v_fmac_f32_e32 v121, v26, v129
	v_fmac_f32_e32 v122, v39, v126
	v_fmac_f32_e32 v123, v35, v127
	v_fmac_f32_e32 v124, v31, v128
	v_fmac_f32_e32 v125, v27, v129
	global_store_dword v136, v110, s[60:61]
	global_store_dword v136, v111, s[60:61] offset:64
	global_store_dword v136, v112, s[60:61] offset:128
	global_store_dword v136, v113, s[60:61] offset:192
	global_store_dword v137, v114, s[60:61]
	global_store_dword v137, v115, s[60:61] offset:64
	global_store_dword v137, v116, s[60:61] offset:128
	global_store_dword v137, v117, s[60:61] offset:192
	global_store_dword v138, v118, s[60:61]
	global_store_dword v138, v119, s[60:61] offset:64
	global_store_dword v138, v120, s[60:61] offset:128
	global_store_dword v138, v121, s[60:61] offset:192
	global_store_dword v139, v122, s[60:61]
	global_store_dword v139, v123, s[60:61] offset:64
	global_store_dword v139, v124, s[60:61] offset:128
	global_store_dword v139, v125, s[60:61] offset:192
	s_waitcnt vmcnt(16)
	v_add_f32_e32 v156, v156, v104
	v_add_f32_e32 v157, v157, v105
	v_add_f32_e32 v158, v158, v106
	v_add_f32_e32 v159, v159, v107
	v_fmac_f32_e32 v140, v20, v156
	v_fmac_f32_e32 v141, v16, v157
	v_fmac_f32_e32 v142, v12, v158
	v_fmac_f32_e32 v143, v8, v159
	v_fmac_f32_e32 v144, v21, v156
	v_fmac_f32_e32 v145, v17, v157
	v_fmac_f32_e32 v146, v13, v158
	v_fmac_f32_e32 v147, v9, v159
	v_fmac_f32_e32 v148, v22, v156
	v_fmac_f32_e32 v149, v18, v157
	v_fmac_f32_e32 v150, v14, v158
	v_fmac_f32_e32 v151, v10, v159
	v_fmac_f32_e32 v152, v23, v156
	v_fmac_f32_e32 v153, v19, v157
	v_fmac_f32_e32 v154, v15, v158
	v_fmac_f32_e32 v155, v11, v159
	global_store_dword v160, v140, s[60:61]
	global_store_dword v160, v141, s[60:61] offset:64
	global_store_dword v160, v142, s[60:61] offset:128
	global_store_dword v160, v143, s[60:61] offset:192
	global_store_dword v161, v144, s[60:61]
	global_store_dword v161, v145, s[60:61] offset:64
	global_store_dword v161, v146, s[60:61] offset:128
	global_store_dword v161, v147, s[60:61] offset:192
	global_store_dword v162, v148, s[60:61]
	global_store_dword v162, v149, s[60:61] offset:64
	global_store_dword v162, v150, s[60:61] offset:128
	global_store_dword v162, v151, s[60:61] offset:192
	global_store_dword v163, v152, s[60:61]
	global_store_dword v163, v153, s[60:61] offset:64
	global_store_dword v163, v154, s[60:61] offset:128
	global_store_dword v163, v155, s[60:61] offset:192
	v_readlane_b32 s20, v253, 55
	v_readlane_b32 s21, v253, 56
	v_readlane_b32 s0, v253, 1
	s_nop 3
	s_add_i32 s16, s16, s0
	s_add_i32 s4, s4, s0
	s_cmpk_gt_i32 s16, 0x1ff
	v_readlane_b32 s1, v253, 2
	s_cbranch_scc1 .LBB0_1519
	s_branch .LBB0_748

.LBB0_1542:
.LBB0_1543:
	v_lshl_add_u64 v[216:217], v[138:139], 0, v[0:1]
	v_lshl_add_u64 v[220:221], v[136:137], 0, v[0:1]
	v_lshl_add_u64 v[224:225], v[134:135], 0, v[0:1]
	v_lshl_add_u64 v[228:229], v[132:133], 0, v[0:1]
	v_lshl_add_u64 v[232:233], v[130:131], 0, v[0:1]
	v_lshl_add_u64 v[236:237], v[128:129], 0, v[0:1]
	global_load_dwordx4 v[216:219], v[216:217], off
	s_nop 0
	global_load_dwordx4 v[220:223], v[220:221], off
	s_nop 0
	global_load_dwordx4 v[224:227], v[224:225], off
	s_nop 0
	global_load_dwordx4 v[228:231], v[228:229], off
	s_nop 0
	global_load_dwordx4 v[232:235], v[232:233], off
	s_nop 0
	global_load_dwordx4 v[236:239], v[236:237], off
	v_lshl_add_u64 v[128:129], v[128:129], 0, s[70:71]
	v_lshl_add_u64 v[130:131], v[130:131], 0, s[70:71]
	v_lshl_add_u64 v[132:133], v[132:133], 0, s[70:71]
	v_lshl_add_u64 v[134:135], v[134:135], 0, s[70:71]
	v_lshl_add_u64 v[136:137], v[136:137], 0, s[70:71]
	v_lshl_add_u64 v[138:139], v[138:139], 0, s[70:71]
	s_barrier
.Lpf_even:
	s_waitcnt vmcnt(6)
	ds_write_b128 v140, v[84:87]
	ds_write_b128 v140, v[92:95] offset:4608
	ds_write_b128 v140, v[100:103] offset:9216
	ds_write_b128 v140, v[108:111] offset:13824
	ds_write_b128 v140, v[116:119] offset:18432
	ds_write_b128 v140, v[124:127] offset:23040
	s_waitcnt lgkmcnt(0)
	s_barrier
	s_add_i32 s98, s4, 64
	s_cmp_lt_u32 s98, s40
	s_cbranch_scc0 .Lpf_even_mma
	v_lshl_add_u64 v[84:85], v[138:139], 0, v[0:1]
	v_lshl_add_u64 v[92:93], v[136:137], 0, v[0:1]
	v_lshl_add_u64 v[100:101], v[134:135], 0, v[0:1]
	v_lshl_add_u64 v[108:109], v[132:133], 0, v[0:1]
	v_lshl_add_u64 v[116:117], v[130:131], 0, v[0:1]
	v_lshl_add_u64 v[124:125], v[128:129], 0, v[0:1]
	global_load_dwordx4 v[84:87], v[84:85], off
	s_nop 0
	global_load_dwordx4 v[92:95], v[92:93], off
	s_nop 0
	global_load_dwordx4 v[100:103], v[100:101], off
	s_nop 0
	global_load_dwordx4 v[108:111], v[108:109], off
	s_nop 0
	global_load_dwordx4 v[116:119], v[116:117], off
	s_nop 0
	global_load_dwordx4 v[124:127], v[124:125], off
.Lpf_even_mma:
	ds_read_b128 v[142:145], v3 offset:18432
	ds_read_b128 v[146:149], v3 offset:20736
	ds_read_b128 v[150:153], v2
	ds_read_b128 v[154:157], v2 offset:4608
	s_setprio 1
	ds_read_b128 v[158:161], v2 offset:9216
	s_waitcnt lgkmcnt(2)
	v_mfma_f32_16x16x32_bf16 v[72:75], v[150:153], v[142:145], v[72:75]
	v_mfma_f32_16x16x32_bf16 v[76:79], v[150:153], v[146:149], v[76:79]
	ds_read_b128 v[150:153], v2 offset:13824
	ds_read_b128 v[162:165], v3 offset:18496
	ds_read_b128 v[166:169], v3 offset:20800
	s_waitcnt lgkmcnt(4)
	v_mfma_f32_16x16x32_bf16 v[80:83], v[154:157], v[142:145], v[80:83]
	v_mfma_f32_16x16x32_bf16 v[88:91], v[154:157], v[146:149], v[88:91]
	ds_read_b128 v[154:157], v2 offset:64
	s_waitcnt lgkmcnt(4)
	v_mfma_f32_16x16x32_bf16 v[96:99], v[158:161], v[142:145], v[96:99]
	v_mfma_f32_16x16x32_bf16 v[104:107], v[158:161], v[146:149], v[104:107]
	ds_read_b128 v[158:161], v2 offset:4672
	s_waitcnt lgkmcnt(4)
	v_mfma_f32_16x16x32_bf16 v[112:115], v[150:153], v[142:145], v[112:115]
	v_mfma_f32_16x16x32_bf16 v[120:123], v[150:153], v[146:149], v[120:123]
	ds_read_b128 v[142:145], v2 offset:9280
	s_waitcnt lgkmcnt(2)
	v_mfma_f32_16x16x32_bf16 v[72:75], v[154:157], v[162:165], v[72:75]
	v_mfma_f32_16x16x32_bf16 v[76:79], v[154:157], v[166:169], v[76:79]
	ds_read_b128 v[146:149], v2 offset:13888
	s_waitcnt lgkmcnt(2)
	v_mfma_f32_16x16x32_bf16 v[80:83], v[158:161], v[162:165], v[80:83]
	v_mfma_f32_16x16x32_bf16 v[88:91], v[158:161], v[166:169], v[88:91]
	s_waitcnt lgkmcnt(1)
	v_mfma_f32_16x16x32_bf16 v[96:99], v[142:145], v[162:165], v[96:99]
	v_mfma_f32_16x16x32_bf16 v[104:107], v[142:145], v[166:169], v[104:107]
	s_waitcnt lgkmcnt(0)
	v_mfma_f32_16x16x32_bf16 v[112:115], v[146:149], v[162:165], v[112:115]
	v_mfma_f32_16x16x32_bf16 v[120:123], v[146:149], v[166:169], v[120:123]
	s_setprio 0
	v_lshl_add_u64 v[128:129], v[128:129], 0, s[70:71]
	v_lshl_add_u64 v[130:131], v[130:131], 0, s[70:71]
	v_lshl_add_u64 v[132:133], v[132:133], 0, s[70:71]
	v_lshl_add_u64 v[134:135], v[134:135], 0, s[70:71]
	v_lshl_add_u64 v[136:137], v[136:137], 0, s[70:71]
	v_lshl_add_u64 v[138:139], v[138:139], 0, s[70:71]
	s_add_i32 s4, s4, 64
	s_cmp_ge_u32 s4, s40
	s_cselect_b64 s[24:25], -1, 0
	s_cbranch_scc1 .Lpf_odd_lastw
	s_waitcnt vmcnt(6)
	s_branch .Lpf_odd_write

.Lpf_odd_write:
	ds_write_b128 v140, v[216:219] offset:27648
	ds_write_b128 v140, v[220:223] offset:32256
	ds_write_b128 v140, v[224:227] offset:36864
	ds_write_b128 v140, v[228:231] offset:41472
	ds_write_b128 v140, v[232:235] offset:46080
	ds_write_b128 v140, v[236:239] offset:50688
	s_waitcnt lgkmcnt(0)
	s_barrier
	s_add_i32 s98, s4, 64
	s_cmp_lt_u32 s98, s40
	s_cbranch_scc0 .Lpf_odd_mma
	v_lshl_add_u64 v[216:217], v[138:139], 0, v[0:1]
	v_lshl_add_u64 v[220:221], v[136:137], 0, v[0:1]
	v_lshl_add_u64 v[224:225], v[134:135], 0, v[0:1]
	v_lshl_add_u64 v[228:229], v[132:133], 0, v[0:1]
	v_lshl_add_u64 v[232:233], v[130:131], 0, v[0:1]
	v_lshl_add_u64 v[236:237], v[128:129], 0, v[0:1]
	global_load_dwordx4 v[216:219], v[216:217], off
	s_nop 0
	global_load_dwordx4 v[220:223], v[220:221], off
	s_nop 0
	global_load_dwordx4 v[224:227], v[224:225], off
	s_nop 0
	global_load_dwordx4 v[228:231], v[228:229], off
	s_nop 0
	global_load_dwordx4 v[232:235], v[232:233], off
	s_nop 0
	global_load_dwordx4 v[236:239], v[236:237], off
.Lpf_odd_mma:
	ds_read_b128 v[142:145], v3 offset:46080
	ds_read_b128 v[146:149], v3 offset:48384
	ds_read_b128 v[150:153], v2 offset:27648
	ds_read_b128 v[154:157], v2 offset:32256
	s_setprio 1
	ds_read_b128 v[158:161], v2 offset:36864
	s_waitcnt lgkmcnt(2)
	v_mfma_f32_16x16x32_bf16 v[72:75], v[150:153], v[142:145], v[72:75]
	v_mfma_f32_16x16x32_bf16 v[76:79], v[150:153], v[146:149], v[76:79]
	ds_read_b128 v[150:153], v2 offset:41472
	ds_read_b128 v[162:165], v3 offset:46144
	ds_read_b128 v[166:169], v3 offset:48448
	s_waitcnt lgkmcnt(4)
	v_mfma_f32_16x16x32_bf16 v[80:83], v[154:157], v[142:145], v[80:83]
	v_mfma_f32_16x16x32_bf16 v[88:91], v[154:157], v[146:149], v[88:91]
	ds_read_b128 v[154:157], v2 offset:27712
	s_waitcnt lgkmcnt(4)
	v_mfma_f32_16x16x32_bf16 v[96:99], v[158:161], v[142:145], v[96:99]
	v_mfma_f32_16x16x32_bf16 v[104:107], v[158:161], v[146:149], v[104:107]
	ds_read_b128 v[158:161], v2 offset:32320
	s_waitcnt lgkmcnt(4)
	v_mfma_f32_16x16x32_bf16 v[112:115], v[150:153], v[142:145], v[112:115]
	v_mfma_f32_16x16x32_bf16 v[120:123], v[150:153], v[146:149], v[120:123]
	ds_read_b128 v[142:145], v2 offset:36928
	s_waitcnt lgkmcnt(2)
	v_mfma_f32_16x16x32_bf16 v[72:75], v[154:157], v[162:165], v[72:75]
	v_mfma_f32_16x16x32_bf16 v[76:79], v[154:157], v[166:169], v[76:79]
	ds_read_b128 v[146:149], v2 offset:41536
	s_waitcnt lgkmcnt(2)
	v_mfma_f32_16x16x32_bf16 v[80:83], v[158:161], v[162:165], v[80:83]
	v_mfma_f32_16x16x32_bf16 v[88:91], v[158:161], v[166:169], v[88:91]
	s_waitcnt lgkmcnt(1)
	v_mfma_f32_16x16x32_bf16 v[96:99], v[142:145], v[162:165], v[96:99]
	v_mfma_f32_16x16x32_bf16 v[104:107], v[142:145], v[166:169], v[104:107]
	s_waitcnt lgkmcnt(0)
	v_mfma_f32_16x16x32_bf16 v[112:115], v[146:149], v[162:165], v[112:115]
	v_mfma_f32_16x16x32_bf16 v[120:123], v[146:149], v[166:169], v[120:123]
	s_setprio 0
	v_lshl_add_u64 v[128:129], v[128:129], 0, s[70:71]
	v_lshl_add_u64 v[130:131], v[130:131], 0, s[70:71]
	v_lshl_add_u64 v[132:133], v[132:133], 0, s[70:71]
	v_lshl_add_u64 v[134:135], v[134:135], 0, s[70:71]
	v_lshl_add_u64 v[136:137], v[136:137], 0, s[70:71]
	v_lshl_add_u64 v[138:139], v[138:139], 0, s[70:71]
	s_andn2_b64 vcc, exec, s[24:25]
	s_add_i32 s4, s4, 64
	s_cbranch_vccz .LBB0_1545
	s_branch .Lpf_even
